# NA smax loop: next K/V tile written to LDS before the PV MFMAs instead of after them; prefetch loads drained at step top on both paths
# baseline (speedup 1.0000x reference)
; template <int DQK, bool NA, bool SMAX, int LDV> ...
;     ...
;     if (it + 2 < nkt) {
;       const int kb = (it + 2) * 64 + ((it + 2) >= 4 ? koff : 0);
; #pragma unroll
;       for (int i = 0; i < NKC; ++i) rk_ld[i] = *(const u32x4*)(Kp + (size_t)(kb + kkey[i]) * ldk + kcc[i] * 8);
;       rv_ld = *(const u32x4*)(Vp + (size_t)(kb + vdv) * LDV + vcc * 8);
;     }
;     __builtin_amdgcn_sched_barrier(0);
.LBB0_1065:
	s_add_i32 s46, s43, 2
	s_cmp_ge_i32 s46, s44
	s_cselect_b64 s[4:5], -1, 0
	s_and_b64 vcc, exec, s[4:5]
	s_cbranch_vccz .Lna_x_ld1
	s_waitcnt vmcnt(0)
	s_branch .LBB0_1067
.Lna_x_ld1:
	s_cmp_lg_u32 s43, 0
	s_cselect_b32 s0, s45, 0
	v_add_u32_e32 v0, s0, v207
	v_subrev_u32_e32 v2, 64, v0
	v_ashrrev_i32_e32 v3, 31, v2
	v_add_u32_e32 v0, s0, v206
	v_lshlrev_b64 v[2:3], 10, v[2:3]
	v_subrev_u32_e32 v0, 64, v0
	v_lshl_add_u64 v[2:3], v[160:161], 0, v[2:3]
	s_waitcnt vmcnt(0)
	v_mad_i64_i32 v[36:37], s[0:1], v0, s63, v[158:159]
	global_load_dwordx4 v[32:35], v[2:3], off
	s_nop 0
	global_load_dwordx4 v[36:39], v[36:37], off

; template <int DQK, bool NA, bool SMAX, int LDV> ...
;     ...
;     if (more) {
;       char* nx = smem + (cur ^ 1) * STG;
; #pragma unroll
;       for (int i = 0; i < NKC; ++i) if (kval[i]) *(u32x4*)(nx + kkey[i] * KSTR + kcc[i] * 16) = rk_wr[i];
;       *(u32x4*)(nx + KBYTES + vdv * VSTR + vcc * 16) = rv_wr;
;     }
.LBB0_1075:
	s_cmp_ge_i32 s43, s42
	s_cbranch_scc1 .Lna_x_nw1
	s_and_saveexec_b64 s[26:27], s[48:49]
	s_cbranch_execz .Lna_x_w1b
	v_add_u32_e32 v3, v204, v205
	ds_write_b128 v3, v[40:43] offset:20480
.Lna_x_w1b:
	s_or_b64 exec, exec, s[26:27]
	ds_write_b128 v162, v[44:47] offset:30720

; template <int DQK, bool NA, bool SMAX, int LDV> ...
;     ...
;     if (it + 2 < nkt) {
;       const int kb = (it + 2) * 64 + ((it + 2) >= 4 ? koff : 0);
; #pragma unroll
;       for (int i = 0; i < NKC; ++i) rk_ld[i] = *(const u32x4*)(Kp + (size_t)(kb + kkey[i]) * ldk + kcc[i] * 8);
;       rv_ld = *(const u32x4*)(Vp + (size_t)(kb + vdv) * LDV + vcc * 8);
;     }
;     ...
;     __syncthreads();
;   };
;   for (int it = 0; it < nkt; it += 2) {
;     step(it, rkA, rvA, rkB, rvB);
;     if (it + 1 < nkt) step(it + 1, rkB, rvB, rkA, rvA);
.LBB0_1079:
	v_add_f32_e32 v152, v152, v2
	v_add_f32_e32 v167, v167, v0
	s_andn2_b64 vcc, exec, s[0:1]
	s_waitcnt lgkmcnt(0)
	s_barrier
	s_cbranch_vccnz .LBB0_1095
	s_add_i32 s0, s43, 3
	s_cmp_ge_i32 s0, s44
	s_cbranch_scc0 .Lna_x_ld2
	s_waitcnt vmcnt(0)
	s_branch .LBB0_1082
.Lna_x_ld2:
	s_cmp_lg_u32 s43, 0
	s_cselect_b32 s0, s45, 0
	v_add_u32_e32 v2, s0, v207
	v_ashrrev_i32_e32 v3, 31, v2
	v_lshlrev_b64 v[2:3], 10, v[2:3]
	v_add_u32_e32 v0, s0, v206
	v_lshl_add_u64 v[2:3], v[160:161], 0, v[2:3]
	s_waitcnt vmcnt(0)
	v_mad_i64_i32 v[44:45], s[0:1], v0, s63, v[158:159]
	global_load_dwordx4 v[40:43], v[2:3], off
	s_nop 0
	global_load_dwordx4 v[44:47], v[44:45], off

; DI unsigned cvt_pk_bf16(float lo, float hi) { f32x2_t v = {lo, hi}; bf16x2_t b = __builtin_convertvector(v, bf16x2_t); return __builtin_bit_cast(unsigned, b); }
; template <int DQK, bool NA, bool SMAX, int LDV> ...
;     ...
; #pragma unroll
;     for (int k2 = 0; k2 < 2; ++k2) {
;       bf16x8 pf[2];
; #pragma unroll
;       for (int qt = 0; qt < 2; ++qt) {
;         u32x4 u;
;         u[0] = cvt_pk_bf16(s[2 * k2][qt][0], s[2 * k2][qt][1]); u[1] = cvt_pk_bf16(s[2 * k2][qt][2], s[2 * k2][qt][3]);
;         u[2] = cvt_pk_bf16(s[2 * k2 + 1][qt][0], s[2 * k2 + 1][qt][1]); u[3] = cvt_pk_bf16(s[2 * k2 + 1][qt][2], s[2 * k2 + 1][qt][3]);
;         pf[qt] = __builtin_bit_cast(bf16x8, u);
;       }
; #pragma unroll
;       for (int d = 0; d < 4; ++d) {
;         o[d][0] = __builtin_amdgcn_mfma_f32_16x16x32_bf16(vfr[k2][d], pf[0], o[d][0], 0, 0, 0);
;         o[d][1] = __builtin_amdgcn_mfma_f32_16x16x32_bf16(vfr[k2][d], pf[1], o[d][1], 0, 0, 0);
;       }
;     }
;     if (more) {
;       char* nx = smem + (cur ^ 1) * STG;
; #pragma unroll
;       for (int i = 0; i < NKC; ++i) if (kval[i]) *(u32x4*)(nx + kkey[i] * KSTR + kcc[i] * 16) = rk_wr[i];
;       *(u32x4*)(nx + KBYTES + vdv * VSTR + vcc * 16) = rv_wr;
;     }
;     __syncthreads();
.LBB0_1090:
	s_cmp_ge_i32 s43, s33
	s_cbranch_scc1 .Lna_x_nw2
	s_and_saveexec_b64 s[0:1], s[48:49]
	s_cbranch_execz .Lna_x_w2b
	v_add_u32_e32 v3, v204, v205
	ds_write_b128 v3, v[32:35]
.Lna_x_w2b:
	s_or_b64 exec, exec, s[0:1]
	ds_write_b128 v162, v[36:39] offset:10240
.Lna_x_nw2:
	v_cvt_pk_bf16_f32 v100, v104, v105
	v_cvt_pk_bf16_f32 v101, v106, v107
	v_cvt_pk_bf16_f32 v102, v108, v109
	v_cvt_pk_bf16_f32 v103, v110, v111
	v_cvt_pk_bf16_f32 v104, v132, v133
	v_cvt_pk_bf16_f32 v105, v134, v135
	v_cvt_pk_bf16_f32 v106, v136, v137
	v_cvt_pk_bf16_f32 v107, v138, v139
	s_waitcnt lgkmcnt(13)
	v_mfma_f32_16x16x32_bf16 v[64:67], v[72:75], v[100:103], v[64:67]
	s_cmp_ge_i32 s43, s33
	v_mfma_f32_16x16x32_bf16 v[48:51], v[72:75], v[104:107], v[48:51]
	v_cvt_pk_bf16_f32 v72, v140, v141
	v_cvt_pk_bf16_f32 v73, v142, v143
	v_cvt_pk_bf16_f32 v74, v144, v145
	s_waitcnt lgkmcnt(12)
	v_mfma_f32_16x16x32_bf16 v[60:63], v[68:71], v[100:103], v[60:63]
	v_cvt_pk_bf16_f32 v75, v146, v147
	v_mfma_f32_16x16x32_bf16 v[12:15], v[68:71], v[104:107], v[12:15]
	v_cvt_pk_bf16_f32 v68, v112, v113
	v_cvt_pk_bf16_f32 v69, v114, v115
	v_cvt_pk_bf16_f32 v70, v128, v129
	s_waitcnt lgkmcnt(10)
	v_mfma_f32_16x16x32_bf16 v[56:59], v[80:83], v[100:103], v[56:59]
	v_cvt_pk_bf16_f32 v71, v130, v131
	v_mfma_f32_16x16x32_bf16 v[8:11], v[80:83], v[104:107], v[8:11]
	s_waitcnt lgkmcnt(8)
	v_mfma_f32_16x16x32_bf16 v[52:55], v[88:91], v[100:103], v[52:55]
	v_mfma_f32_16x16x32_bf16 v[4:7], v[88:91], v[104:107], v[4:7]
	s_waitcnt lgkmcnt(6)
	v_mfma_f32_16x16x32_bf16 v[64:67], v[76:79], v[68:71], v[64:67]
	v_mfma_f32_16x16x32_bf16 v[48:51], v[76:79], v[72:75], v[48:51]
	s_waitcnt lgkmcnt(4)
	v_mfma_f32_16x16x32_bf16 v[60:63], v[84:87], v[68:71], v[60:63]
	v_mfma_f32_16x16x32_bf16 v[12:15], v[84:87], v[72:75], v[12:15]
	s_waitcnt lgkmcnt(2)
	v_mfma_f32_16x16x32_bf16 v[56:59], v[92:95], v[68:71], v[56:59]
	v_mfma_f32_16x16x32_bf16 v[8:11], v[92:95], v[72:75], v[8:11]
	s_waitcnt lgkmcnt(0)
	v_mfma_f32_16x16x32_bf16 v[52:55], v[96:99], v[68:71], v[52:55]
	v_mfma_f32_16x16x32_bf16 v[4:7], v[96:99], v[72:75], v[4:7]
.LBB0_1094:
	v_add_f32_e32 v152, v152, v2
	v_add_f32_e32 v167, v167, v0
	s_waitcnt lgkmcnt(0)
	s_barrier
